# grid barrier release: waiting workgroups poll the cross-XCD release word directly (one hop fewer: no leader poll -> per-XCD word -> waiter poll)
# speedup vs baseline: 1.0175x; 1.0090x over previous
; __device__ __forceinline__ unsigned xb_ld(unsigned* p)              { return __hip_atomic_load(p, __ATOMIC_RELAXED, __HIP_MEMORY_SCOPE_AGENT); }
; __device__ __forceinline__ unsigned xb_add(unsigned* p, unsigned v) { return __hip_atomic_fetch_add(p, v, __ATOMIC_RELAXED, __HIP_MEMORY_SCOPE_AGENT); }
; #define XB_SPIN(cond, bar) do { unsigned _sp = 0; while (cond) { __builtin_amdgcn_s_sleep(1); \
;     if ((++_sp & 255u) == 0u) { if (xb_ld(&(bar)[XB_TMO])) break; if (_sp > XB_SPIN_CAP) { atomicAdd(&(bar)[XB_TMO], 1u); break; } } } } while (0)
; __device__ __forceinline__ void xcd_barrier(const XcdBarrier& b) {
;     ...
;         const unsigned old = xb_add(&bar[XB_XSUB(b.x)], 1u);
;         const unsigned gen = old / nloc;
;         if (old + 1u == (gen + 1u) * nloc) {
;             __builtin_amdgcn_fence(__ATOMIC_RELEASE, "agent");
;             asm volatile("s_waitcnt vmcnt(0)" ::: "memory");
;             const unsigned og = xb_add(&bar[XB_TOP], 1u);
;             const unsigned tg = og / nx;
;             if (og + 1u == (tg + 1u) * nx) xb_add(&bar[XB_TOPGEN], 1u);
;             else XB_SPIN(xb_ld(&bar[XB_TOPGEN]) == tg, bar);
;             __builtin_amdgcn_fence(__ATOMIC_ACQUIRE, "agent");
;             xb_add(&bar[XB_XGEN(b.x)], 1u);
;             asm volatile("s_waitcnt vmcnt(0)" ::: "memory");
;         } else {
;             XB_SPIN(xb_ld(&bar[XB_XGEN(b.x)]) == gen, bar);
.LBB0_50:
	s_or_b64 exec, exec, s[8:9]
	v_cvt_f32_u32_e32 v4, v2
	s_waitcnt vmcnt(0)
	v_readfirstlane_b32 s6, v3
	v_sub_u32_e32 v3, 0, v2
	v_rcp_iflag_f32_e32 v4, v4
	v_add_u32_e32 v5, s6, v1
	v_mul_f32_e32 v4, 0x4f7ffffe, v4
	v_cvt_u32_f32_e32 v4, v4
	v_mul_lo_u32 v1, v3, v4
	v_mul_hi_u32 v1, v4, v1
	v_add_u32_e32 v1, v4, v1
	v_mul_hi_u32 v1, v5, v1
	v_mul_lo_u32 v3, v1, v2
	v_sub_u32_e32 v3, v5, v3
	v_add_u32_e32 v4, 1, v1
	v_cmp_ge_u32_e32 vcc, v3, v2
	s_nop 1
	v_cndmask_b32_e32 v1, v1, v4, vcc
	v_sub_u32_e32 v4, v3, v2
	v_cndmask_b32_e32 v3, v3, v4, vcc
	v_add_u32_e32 v4, 1, v1
	v_cmp_ge_u32_e32 vcc, v3, v2
	v_add_u32_e32 v3, 1, v5
	s_nop 0
	v_cndmask_b32_e32 v1, v1, v4, vcc
	v_mul_lo_u32 v4, v2, v1
	v_add_u32_e32 v2, v4, v2
	v_cmp_ne_u32_e32 vcc, v3, v2
	s_and_saveexec_b64 s[6:7], vcc
	s_xor_b64 s[6:7], exec, s[6:7]
	s_cbranch_execz .LBB0_64
	buffer_inv sc1
	s_waitcnt lgkmcnt(0)
	s_add_u32 s12, s50, 0xfc3500
	s_addc_u32 s13, s51, 0
	v_mov_b32_e32 v0, 0
	global_load_dword v0, v0, s[12:13] sc1
	s_waitcnt vmcnt(0)
	v_cmp_eq_u32_e32 vcc, v0, v1
	s_and_saveexec_b64 s[8:9], vcc
	s_cbranch_execz .LBB0_63
	s_add_u32 s10, s50, 0xfc0200
	s_addc_u32 s11, s51, 0
	s_mov_b32 s26, 1
	s_mov_b64 s[14:15], 0
	v_mov_b32_e32 v0, 0
	s_branch .LBB0_54

; __device__ __forceinline__ unsigned xb_ld(unsigned* p)              { return __hip_atomic_load(p, __ATOMIC_RELAXED, __HIP_MEMORY_SCOPE_AGENT); }
; __device__ __forceinline__ unsigned xb_add(unsigned* p, unsigned v) { return __hip_atomic_fetch_add(p, v, __ATOMIC_RELAXED, __HIP_MEMORY_SCOPE_AGENT); }
; #define XB_SPIN(cond, bar) do { unsigned _sp = 0; while (cond) { __builtin_amdgcn_s_sleep(1); \
;     if ((++_sp & 255u) == 0u) { if (xb_ld(&(bar)[XB_TMO])) break; if (_sp > XB_SPIN_CAP) { atomicAdd(&(bar)[XB_TMO], 1u); break; } } } } while (0)
; __device__ __forceinline__ void xcd_barrier(const XcdBarrier& b) {
;     ...
;         const unsigned old = xb_add(&bar[XB_XSUB(b.x)], 1u);
;         const unsigned gen = old / nloc;
;         if (old + 1u == (gen + 1u) * nloc) {
;             __builtin_amdgcn_fence(__ATOMIC_RELEASE, "agent");
;             asm volatile("s_waitcnt vmcnt(0)" ::: "memory");
;             const unsigned og = xb_add(&bar[XB_TOP], 1u);
;             const unsigned tg = og / nx;
;             if (og + 1u == (tg + 1u) * nx) xb_add(&bar[XB_TOPGEN], 1u);
;             else XB_SPIN(xb_ld(&bar[XB_TOPGEN]) == tg, bar);
;             __builtin_amdgcn_fence(__ATOMIC_ACQUIRE, "agent");
;             xb_add(&bar[XB_XGEN(b.x)], 1u);
;             asm volatile("s_waitcnt vmcnt(0)" ::: "memory");
;         } else {
;             XB_SPIN(xb_ld(&bar[XB_XGEN(b.x)]) == gen, bar);
.LBB0_376:
	s_or_b64 exec, exec, s[8:9]
	v_cvt_f32_u32_e32 v4, v2
	s_waitcnt vmcnt(0)
	v_readfirstlane_b32 s6, v3
	v_sub_u32_e32 v3, 0, v2
	v_rcp_iflag_f32_e32 v4, v4
	v_add_u32_e32 v5, s6, v1
	v_mul_f32_e32 v4, 0x4f7ffffe, v4
	v_cvt_u32_f32_e32 v4, v4
	v_mul_lo_u32 v1, v3, v4
	v_mul_hi_u32 v1, v4, v1
	v_add_u32_e32 v1, v4, v1
	v_mul_hi_u32 v1, v5, v1
	v_mul_lo_u32 v3, v1, v2
	v_sub_u32_e32 v3, v5, v3
	v_add_u32_e32 v4, 1, v1
	v_cmp_ge_u32_e32 vcc, v3, v2
	s_nop 1
	v_cndmask_b32_e32 v1, v1, v4, vcc
	v_sub_u32_e32 v4, v3, v2
	v_cndmask_b32_e32 v3, v3, v4, vcc
	v_add_u32_e32 v4, 1, v1
	v_cmp_ge_u32_e32 vcc, v3, v2
	v_add_u32_e32 v3, 1, v5
	s_nop 0
	v_cndmask_b32_e32 v1, v1, v4, vcc
	v_mul_lo_u32 v4, v2, v1
	v_add_u32_e32 v2, v4, v2
	v_cmp_ne_u32_e32 vcc, v3, v2
	s_and_saveexec_b64 s[6:7], vcc
	s_xor_b64 s[6:7], exec, s[6:7]
	s_cbranch_execz .LBB0_390
	buffer_inv sc1
	s_waitcnt lgkmcnt(0)
	s_add_u32 s12, s50, 0xfc3500
	s_addc_u32 s13, s51, 0
	v_mov_b32_e32 v0, 0
	global_load_dword v0, v0, s[12:13] sc1
	s_waitcnt vmcnt(0)
	v_cmp_eq_u32_e32 vcc, v0, v1
	s_and_saveexec_b64 s[8:9], vcc
	s_cbranch_execz .LBB0_389
	s_add_u32 s10, s50, 0xfc0200
	s_addc_u32 s11, s51, 0
	s_mov_b32 s28, 1
	s_mov_b64 s[14:15], 0
	v_mov_b32_e32 v0, 0
	s_branch .LBB0_380

; __device__ __forceinline__ unsigned xb_ld(unsigned* p)              { return __hip_atomic_load(p, __ATOMIC_RELAXED, __HIP_MEMORY_SCOPE_AGENT); }
; __device__ __forceinline__ unsigned xb_add(unsigned* p, unsigned v) { return __hip_atomic_fetch_add(p, v, __ATOMIC_RELAXED, __HIP_MEMORY_SCOPE_AGENT); }
; #define XB_SPIN(cond, bar) do { unsigned _sp = 0; while (cond) { __builtin_amdgcn_s_sleep(1); \
;     if ((++_sp & 255u) == 0u) { if (xb_ld(&(bar)[XB_TMO])) break; if (_sp > XB_SPIN_CAP) { atomicAdd(&(bar)[XB_TMO], 1u); break; } } } } while (0)
; __device__ __forceinline__ void xcd_barrier(const XcdBarrier& b) {
;     ...
;         const unsigned old = xb_add(&bar[XB_XSUB(b.x)], 1u);
;         const unsigned gen = old / nloc;
;         if (old + 1u == (gen + 1u) * nloc) {
;             __builtin_amdgcn_fence(__ATOMIC_RELEASE, "agent");
;             asm volatile("s_waitcnt vmcnt(0)" ::: "memory");
;             const unsigned og = xb_add(&bar[XB_TOP], 1u);
;             const unsigned tg = og / nx;
;             if (og + 1u == (tg + 1u) * nx) xb_add(&bar[XB_TOPGEN], 1u);
;             else XB_SPIN(xb_ld(&bar[XB_TOPGEN]) == tg, bar);
;             __builtin_amdgcn_fence(__ATOMIC_ACQUIRE, "agent");
;             xb_add(&bar[XB_XGEN(b.x)], 1u);
;             asm volatile("s_waitcnt vmcnt(0)" ::: "memory");
;         } else {
;             XB_SPIN(xb_ld(&bar[XB_XGEN(b.x)]) == gen, bar);
.LBB0_492:
	s_or_b64 exec, exec, s[8:9]
	v_cvt_f32_u32_e32 v4, v2
	s_waitcnt vmcnt(0)
	v_readfirstlane_b32 s6, v3
	v_sub_u32_e32 v3, 0, v2
	v_rcp_iflag_f32_e32 v4, v4
	v_add_u32_e32 v5, s6, v1
	v_mul_f32_e32 v4, 0x4f7ffffe, v4
	v_cvt_u32_f32_e32 v4, v4
	v_mul_lo_u32 v1, v3, v4
	v_mul_hi_u32 v1, v4, v1
	v_add_u32_e32 v1, v4, v1
	v_mul_hi_u32 v1, v5, v1
	v_mul_lo_u32 v3, v1, v2
	v_sub_u32_e32 v3, v5, v3
	v_add_u32_e32 v4, 1, v1
	v_cmp_ge_u32_e32 vcc, v3, v2
	s_nop 1
	v_cndmask_b32_e32 v1, v1, v4, vcc
	v_sub_u32_e32 v4, v3, v2
	v_cndmask_b32_e32 v3, v3, v4, vcc
	v_add_u32_e32 v4, 1, v1
	v_cmp_ge_u32_e32 vcc, v3, v2
	v_add_u32_e32 v3, 1, v5
	s_nop 0
	v_cndmask_b32_e32 v1, v1, v4, vcc
	v_mul_lo_u32 v4, v2, v1
	v_add_u32_e32 v2, v4, v2
	v_cmp_ne_u32_e32 vcc, v3, v2
	s_and_saveexec_b64 s[6:7], vcc
	s_xor_b64 s[6:7], exec, s[6:7]
	s_cbranch_execz .LBB0_506
	buffer_inv sc1
	s_waitcnt lgkmcnt(0)
	s_add_u32 s12, s50, 0xfc3500
	s_addc_u32 s13, s51, 0
	v_mov_b32_e32 v0, 0
	global_load_dword v0, v0, s[12:13] sc1
	s_waitcnt vmcnt(0)
	v_cmp_eq_u32_e32 vcc, v0, v1
	s_and_saveexec_b64 s[8:9], vcc
	s_cbranch_execz .LBB0_505
	s_add_u32 s10, s50, 0xfc0200
	s_addc_u32 s11, s51, 0
	s_mov_b32 s30, 1
	s_mov_b64 s[14:15], 0
	v_mov_b32_e32 v0, 0
	s_branch .LBB0_496

; __device__ __forceinline__ unsigned xb_ld(unsigned* p)              { return __hip_atomic_load(p, __ATOMIC_RELAXED, __HIP_MEMORY_SCOPE_AGENT); }
; __device__ __forceinline__ unsigned xb_add(unsigned* p, unsigned v) { return __hip_atomic_fetch_add(p, v, __ATOMIC_RELAXED, __HIP_MEMORY_SCOPE_AGENT); }
; #define XB_SPIN(cond, bar) do { unsigned _sp = 0; while (cond) { __builtin_amdgcn_s_sleep(1); \
;     if ((++_sp & 255u) == 0u) { if (xb_ld(&(bar)[XB_TMO])) break; if (_sp > XB_SPIN_CAP) { atomicAdd(&(bar)[XB_TMO], 1u); break; } } } } while (0)
; __device__ __forceinline__ void xcd_barrier(const XcdBarrier& b) {
;     ...
;         const unsigned old = xb_add(&bar[XB_XSUB(b.x)], 1u);
;         const unsigned gen = old / nloc;
;         if (old + 1u == (gen + 1u) * nloc) {
;             __builtin_amdgcn_fence(__ATOMIC_RELEASE, "agent");
;             asm volatile("s_waitcnt vmcnt(0)" ::: "memory");
;             const unsigned og = xb_add(&bar[XB_TOP], 1u);
;             const unsigned tg = og / nx;
;             if (og + 1u == (tg + 1u) * nx) xb_add(&bar[XB_TOPGEN], 1u);
;             else XB_SPIN(xb_ld(&bar[XB_TOPGEN]) == tg, bar);
;             __builtin_amdgcn_fence(__ATOMIC_ACQUIRE, "agent");
;             xb_add(&bar[XB_XGEN(b.x)], 1u);
;             asm volatile("s_waitcnt vmcnt(0)" ::: "memory");
;         } else {
;             XB_SPIN(xb_ld(&bar[XB_XGEN(b.x)]) == gen, bar);
.LBB0_586:
	s_or_b64 exec, exec, s[14:15]
	v_cvt_f32_u32_e32 v4, v2
	s_waitcnt vmcnt(0)
	v_readfirstlane_b32 s8, v3
	v_sub_u32_e32 v3, 0, v2
	v_rcp_iflag_f32_e32 v4, v4
	v_add_u32_e32 v5, s8, v1
	v_mul_f32_e32 v4, 0x4f7ffffe, v4
	v_cvt_u32_f32_e32 v4, v4
	v_mul_lo_u32 v1, v3, v4
	v_mul_hi_u32 v1, v4, v1
	v_add_u32_e32 v1, v4, v1
	v_mul_hi_u32 v1, v5, v1
	v_mul_lo_u32 v3, v1, v2
	v_sub_u32_e32 v3, v5, v3
	v_add_u32_e32 v4, 1, v1
	v_cmp_ge_u32_e32 vcc, v3, v2
	s_nop 1
	v_cndmask_b32_e32 v1, v1, v4, vcc
	v_sub_u32_e32 v4, v3, v2
	v_cndmask_b32_e32 v3, v3, v4, vcc
	v_add_u32_e32 v4, 1, v1
	v_cmp_ge_u32_e32 vcc, v3, v2
	v_add_u32_e32 v3, 1, v5
	s_nop 0
	v_cndmask_b32_e32 v1, v1, v4, vcc
	v_mul_lo_u32 v4, v2, v1
	v_add_u32_e32 v2, v4, v2
	v_cmp_ne_u32_e32 vcc, v3, v2
	s_and_saveexec_b64 s[8:9], vcc
	s_xor_b64 s[8:9], exec, s[8:9]
	s_cbranch_execz .LBB0_600
	buffer_inv sc1
	s_waitcnt lgkmcnt(0)
	s_add_u32 s24, s50, 0xfc3500
	s_addc_u32 s25, s51, 0
	v_mov_b32_e32 v0, 0
	global_load_dword v0, v0, s[24:25] sc1
	s_waitcnt vmcnt(0)
	v_cmp_eq_u32_e32 vcc, v0, v1
	s_and_saveexec_b64 s[14:15], vcc
	s_cbranch_execz .LBB0_599
	s_add_u32 s16, s50, 0xfc0200
	s_addc_u32 s17, s51, 0
	s_mov_b32 s33, 1
	s_mov_b64 s[26:27], 0
	v_mov_b32_e32 v0, 0
	s_branch .LBB0_590

; __device__ __forceinline__ unsigned xb_ld(unsigned* p)              { return __hip_atomic_load(p, __ATOMIC_RELAXED, __HIP_MEMORY_SCOPE_AGENT); }
; __device__ __forceinline__ unsigned xb_add(unsigned* p, unsigned v) { return __hip_atomic_fetch_add(p, v, __ATOMIC_RELAXED, __HIP_MEMORY_SCOPE_AGENT); }
; #define XB_SPIN(cond, bar) do { unsigned _sp = 0; while (cond) { __builtin_amdgcn_s_sleep(1); \
;     if ((++_sp & 255u) == 0u) { if (xb_ld(&(bar)[XB_TMO])) break; if (_sp > XB_SPIN_CAP) { atomicAdd(&(bar)[XB_TMO], 1u); break; } } } } while (0)
; __device__ __forceinline__ void xcd_barrier(const XcdBarrier& b) {
;     ...
;         const unsigned old = xb_add(&bar[XB_XSUB(b.x)], 1u);
;         const unsigned gen = old / nloc;
;         if (old + 1u == (gen + 1u) * nloc) {
;             __builtin_amdgcn_fence(__ATOMIC_RELEASE, "agent");
;             asm volatile("s_waitcnt vmcnt(0)" ::: "memory");
;             const unsigned og = xb_add(&bar[XB_TOP], 1u);
;             const unsigned tg = og / nx;
;             if (og + 1u == (tg + 1u) * nx) xb_add(&bar[XB_TOPGEN], 1u);
;             else XB_SPIN(xb_ld(&bar[XB_TOPGEN]) == tg, bar);
;             __builtin_amdgcn_fence(__ATOMIC_ACQUIRE, "agent");
;             xb_add(&bar[XB_XGEN(b.x)], 1u);
;             asm volatile("s_waitcnt vmcnt(0)" ::: "memory");
;         } else {
;             XB_SPIN(xb_ld(&bar[XB_XGEN(b.x)]) == gen, bar);
.LBB0_662:
	s_or_b64 exec, exec, s[14:15]
	v_cvt_f32_u32_e32 v4, v2
	s_waitcnt vmcnt(0)
	v_readfirstlane_b32 s3, v3
	v_sub_u32_e32 v3, 0, v2
	v_rcp_iflag_f32_e32 v4, v4
	v_add_u32_e32 v5, s3, v1
	v_mul_f32_e32 v4, 0x4f7ffffe, v4
	v_cvt_u32_f32_e32 v4, v4
	v_mul_lo_u32 v1, v3, v4
	v_mul_hi_u32 v1, v4, v1
	v_add_u32_e32 v1, v4, v1
	v_mul_hi_u32 v1, v5, v1
	v_mul_lo_u32 v3, v1, v2
	v_sub_u32_e32 v3, v5, v3
	v_add_u32_e32 v4, 1, v1
	v_cmp_ge_u32_e32 vcc, v3, v2
	s_nop 1
	v_cndmask_b32_e32 v1, v1, v4, vcc
	v_sub_u32_e32 v4, v3, v2
	v_cndmask_b32_e32 v3, v3, v4, vcc
	v_add_u32_e32 v4, 1, v1
	v_cmp_ge_u32_e32 vcc, v3, v2
	v_add_u32_e32 v3, 1, v5
	s_nop 0
	v_cndmask_b32_e32 v1, v1, v4, vcc
	v_mul_lo_u32 v4, v2, v1
	v_add_u32_e32 v2, v4, v2
	v_cmp_ne_u32_e32 vcc, v3, v2
	s_and_saveexec_b64 s[8:9], vcc
	s_xor_b64 s[8:9], exec, s[8:9]
	s_cbranch_execz .LBB0_676
	buffer_inv sc1
	s_waitcnt lgkmcnt(0)
	s_add_u32 s18, s50, 0xfc3500
	s_addc_u32 s19, s51, 0
	v_mov_b32_e32 v0, 0
	global_load_dword v0, v0, s[18:19] sc1
	s_waitcnt vmcnt(0)
	v_cmp_eq_u32_e32 vcc, v0, v1
	s_and_saveexec_b64 s[14:15], vcc
	s_cbranch_execz .LBB0_675
	s_add_u32 s16, s50, 0xfc0200
	s_addc_u32 s17, s51, 0
	s_mov_b32 s3, 1
	s_mov_b64 s[22:23], 0
	v_mov_b32_e32 v0, 0
	s_branch .LBB0_666
